# latent attention unit: removed the early vmcnt(0) so the sink and second V-tile loads overlap the first Q/K/V round trip
# speedup vs baseline: 1.0033x; 1.0033x over previous
.LBB0_549:
	v_mov_b32_e32 v17, 0
	s_andn2_b64 vcc, exec, s[12:13]
	v_mov_b32_e32 v16, v17
	v_mov_b32_e32 v15, v17
	v_mov_b32_e32 v14, v17
	v_mov_b32_e32 v13, v17
	v_mov_b32_e32 v12, v17
	v_mov_b32_e32 v11, v17
	v_mov_b32_e32 v10, v17
	v_mov_b32_e32 v9, v17
	v_mov_b32_e32 v8, v17
	v_mov_b32_e32 v7, v17
	v_mov_b32_e32 v6, v17
	v_mov_b32_e32 v5, v17
	v_mov_b32_e32 v4, v17
	v_mov_b32_e32 v3, v17
	v_mov_b32_e32 v2, v17
	v_mov_b32_e32 v33, v17
	v_mov_b32_e32 v32, v17
	v_mov_b32_e32 v31, v17
	v_mov_b32_e32 v30, v17
	v_mov_b32_e32 v29, v17
	v_mov_b32_e32 v28, v17
	v_mov_b32_e32 v27, v17
	v_mov_b32_e32 v26, v17
	v_mov_b32_e32 v25, v17
	v_mov_b32_e32 v24, v17
	v_mov_b32_e32 v23, v17
	v_mov_b32_e32 v22, v17
	v_mov_b32_e32 v21, v17
	v_mov_b32_e32 v20, v17
	v_mov_b32_e32 v19, v17
	v_mov_b32_e32 v18, v17
	v_mov_b32_e32 v106, v237
	s_cbranch_vccnz .Lattn_empty
	s_and_b32 s11, s30, 63
	s_min_u32 s11, s11, 2
	s_lshl_b32 s12, s11, 6
	s_sub_i32 s44, 0, s11
	s_ashr_i32 s11, s10, 31
	s_add_i32 s37, s36, 4
	s_lshl_b64 s[10:11], s[10:11], 2
	s_add_u32 s10, s23, s10
	s_addc_u32 s11, s24, s11
	v_add_u32_e32 v4, s17, v151
	v_mov_b64_e32 v[2:3], s[38:39]
	global_load_dword v0, v1, s[10:11]
	v_mad_i64_i32 v[2:3], s[10:11], v4, s91, v[2:3]
	v_lshl_add_u64 v[2:3], v[2:3], 0, s[96:97]
	v_lshl_add_u64 v[2:3], s[42:43], 1, v[2:3]
	global_load_dwordx4 v[94:97], v[2:3], off offset:2304
	s_lshl_b32 s49, s16, 8
	s_sub_i32 s47, 0, s36
	s_addk_i32 s49, 0x4000
	v_mov_b32_e32 v2, 0
	s_add_u32 s10, s28, s96
	s_mov_b32 s52, 0
	v_lshl_add_u64 v[100:101], v[158:159], 0, s[96:97]
	v_mov_b32_e32 v111, v237
	s_mov_b32 s45, 0
	v_mov_b32_e32 v3, v2
	v_mov_b32_e32 v4, v2
	v_mov_b32_e32 v5, v2
	v_mov_b32_e32 v6, v2
	v_mov_b32_e32 v7, v2
	v_mov_b32_e32 v8, v2
	v_mov_b32_e32 v9, v2
	v_mov_b32_e32 v10, v2
	v_mov_b32_e32 v11, v2
	v_mov_b32_e32 v12, v2
	v_mov_b32_e32 v13, v2
	v_mov_b32_e32 v14, v2
	v_mov_b32_e32 v15, v2
	v_mov_b32_e32 v16, v2
	v_mov_b32_e32 v17, v2
	v_mov_b32_e32 v18, v2
	v_mov_b32_e32 v19, v2
	v_mov_b32_e32 v20, v2
	v_mov_b32_e32 v21, v2
	v_mov_b32_e32 v22, v2
	v_mov_b32_e32 v23, v2
	v_mov_b32_e32 v24, v2
	v_mov_b32_e32 v25, v2
	v_mov_b32_e32 v26, v2
	v_mov_b32_e32 v27, v2
	v_mov_b32_e32 v28, v2
	v_mov_b32_e32 v29, v2
	v_mov_b32_e32 v30, v2
	v_mov_b32_e32 v31, v2
	v_mov_b32_e32 v32, v2
	v_subrev_u32_e32 v99, s12, v155
	s_addc_u32 s11, s29, 0
	v_mov_b32_e32 v33, v2
	s_waitcnt vmcnt(1)
	v_mul_f32_e32 v0, 0x3fb8aa3b, v0

.Lattn_empty:
	s_waitcnt vmcnt(0)
	s_branch .LBB0_386
